# C38: C28 with the 16 redundant back-to-back s_setprio 0 / s_setprio 1 pairs between the two MFMA clusters of the GEMM K-loops removed (loop-edge / issue-slot trim)
# speedup vs baseline: 1.0073x; 1.0073x over previous
.LBB0_106:
	s_add_u32 s20, s18, 0x100
	s_addc_u32 s21, s19, 0
	s_add_i32 s47, 0, 0x10000
	s_cmp_eq_u32 s46, 12
	s_cselect_b32 s25, s15, s21
	s_cselect_b32 s24, s14, s20
	v_add_u32_e32 v0, s47, v242
	s_cselect_b32 s23, s43, s45
	s_cselect_b32 s22, s42, s44
	s_add_i32 s48, 0, 0x14000
	ds_read_b128 v[98:101], v0
	ds_read_b128 v[110:113], v0 offset:1024
	ds_read_b128 v[122:125], v0 offset:2048
	ds_read_b128 v[130:133], v0 offset:3072
	v_add_u32_e32 v0, s48, v242
	ds_read_b128 v[138:141], v0
	ds_read_b128 v[142:145], v0 offset:1024
	ds_read_b128 v[146:149], v0 offset:2048
	ds_read_b128 v[150:153], v0 offset:3072
	v_lshl_add_u64 v[208:209], s[18:19], 0, v[204:205]
	s_add_i32 m0, s27, 0xc000
	ds_read_b128 v[158:161], v247
	ds_read_b128 v[166:169], v247 offset:1024
	ds_read_b128 v[170:173], v247 offset:2048
	ds_read_b128 v[174:177], v247 offset:3072
	ds_read_b128 v[178:181], v247 offset:4096
	ds_read_b128 v[182:185], v247 offset:5120
	ds_read_b128 v[186:189], v247 offset:6144
	ds_read_b128 v[190:193], v247 offset:7168
	global_load_lds_dwordx4 v[208:209], off
	v_lshl_add_u64 v[208:209], s[18:19], 0, v[206:207]
	s_add_i32 m0, s27, 0xe000
	s_nop 0
	global_load_lds_dwordx4 v[208:209], off
	s_waitcnt vmcnt(8)
	s_waitcnt lgkmcnt(0)
	s_barrier
	s_setprio 1
	s_waitcnt lgkmcnt(0)
	v_mfma_f32_16x16x32_bf16 v[162:165], v[98:101], v[158:161], v[162:165]
	v_mfma_f32_16x16x32_bf16 v[154:157], v[122:125], v[158:161], v[154:157]
	v_mfma_f32_16x16x32_bf16 v[118:121], v[98:101], v[170:173], v[118:121]
	v_mfma_f32_16x16x32_bf16 v[114:117], v[122:125], v[170:173], v[114:117]
	v_mfma_f32_16x16x32_bf16 v[94:97], v[98:101], v[178:181], v[94:97]
	v_mfma_f32_16x16x32_bf16 v[90:93], v[122:125], v[178:181], v[90:93]
	v_mfma_f32_16x16x32_bf16 v[78:81], v[98:101], v[186:189], v[78:81]
	v_mfma_f32_16x16x32_bf16 v[74:77], v[122:125], v[186:189], v[74:77]
	v_mfma_f32_16x16x32_bf16 v[162:165], v[110:113], v[166:169], v[162:165]
	v_mfma_f32_16x16x32_bf16 v[154:157], v[130:133], v[166:169], v[154:157]
	v_mfma_f32_16x16x32_bf16 v[118:121], v[110:113], v[174:177], v[118:121]
	v_mfma_f32_16x16x32_bf16 v[114:117], v[130:133], v[174:177], v[114:117]
	v_mfma_f32_16x16x32_bf16 v[94:97], v[110:113], v[182:185], v[94:97]
	v_mfma_f32_16x16x32_bf16 v[90:93], v[130:133], v[182:185], v[90:93]
	v_mfma_f32_16x16x32_bf16 v[78:81], v[110:113], v[190:193], v[78:81]
	v_mfma_f32_16x16x32_bf16 v[74:77], v[130:133], v[190:193], v[74:77]
	v_mfma_f32_16x16x32_bf16 v[134:137], v[138:141], v[158:161], v[134:137]
	v_mfma_f32_16x16x32_bf16 v[126:129], v[146:149], v[158:161], v[126:129]
	v_mfma_f32_16x16x32_bf16 v[106:109], v[138:141], v[170:173], v[106:109]
	v_mfma_f32_16x16x32_bf16 v[102:105], v[146:149], v[170:173], v[102:105]
	v_mfma_f32_16x16x32_bf16 v[86:89], v[138:141], v[178:181], v[86:89]
	v_mfma_f32_16x16x32_bf16 v[82:85], v[146:149], v[178:181], v[82:85]
	v_mfma_f32_16x16x32_bf16 v[70:73], v[138:141], v[186:189], v[70:73]
	v_mfma_f32_16x16x32_bf16 v[66:69], v[146:149], v[186:189], v[66:69]
	v_mfma_f32_16x16x32_bf16 v[134:137], v[142:145], v[166:169], v[134:137]
	v_mfma_f32_16x16x32_bf16 v[126:129], v[150:153], v[166:169], v[126:129]
	v_mfma_f32_16x16x32_bf16 v[106:109], v[142:145], v[174:177], v[106:109]
	v_mfma_f32_16x16x32_bf16 v[102:105], v[150:153], v[174:177], v[102:105]
	v_mfma_f32_16x16x32_bf16 v[86:89], v[142:145], v[182:185], v[86:89]
	v_mfma_f32_16x16x32_bf16 v[82:85], v[150:153], v[182:185], v[82:85]
	v_mfma_f32_16x16x32_bf16 v[70:73], v[142:145], v[190:193], v[70:73]
	v_mfma_f32_16x16x32_bf16 v[66:69], v[150:153], v[190:193], v[66:69]
	s_setprio 0
	s_barrier
	s_add_i32 s18, s47, s26
	v_lshl_add_u64 v[208:209], s[22:23], 0, v[198:199]
	s_mov_b32 m0, s18
	ds_read_b128 v[158:161], v247 offset:16384
	ds_read_b128 v[166:169], v247 offset:17408
	ds_read_b128 v[170:173], v247 offset:18432
	ds_read_b128 v[174:177], v247 offset:19456
	ds_read_b128 v[178:181], v247 offset:20480
	ds_read_b128 v[182:185], v247 offset:21504
	ds_read_b128 v[186:189], v247 offset:22528
	ds_read_b128 v[190:193], v247 offset:23552
	global_load_lds_dwordx4 v[208:209], off
	s_add_i32 m0, s18, 0x2000
	s_add_u32 s18, s22, 0x40000
	v_lshl_add_u64 v[210:211], s[22:23], 0, v[196:197]
	s_addc_u32 s19, s23, 0
	s_add_i32 s47, s48, s26
	global_load_lds_dwordx4 v[210:211], off
	v_lshl_add_u64 v[212:213], s[18:19], 0, v[198:199]
	s_mov_b32 m0, s47
	v_lshl_add_u64 v[214:215], s[24:25], 0, v[196:197]
	global_load_lds_dwordx4 v[212:213], off
	v_lshl_add_u64 v[212:213], s[18:19], 0, v[196:197]
	s_add_i32 m0, s47, 0x2000
	s_nop 0
	global_load_lds_dwordx4 v[212:213], off
	v_lshl_add_u64 v[212:213], s[24:25], 0, v[198:199]
	s_mov_b32 m0, s27
	s_nop 0
	global_load_lds_dwordx4 v[212:213], off
	s_mov_b32 m0, s28
	s_nop 0
	global_load_lds_dwordx4 v[214:215], off
	s_waitcnt vmcnt(8)
	s_waitcnt lgkmcnt(0)
	s_barrier
	s_setprio 1
	s_waitcnt lgkmcnt(0)
	v_mfma_f32_16x16x32_bf16 v[62:65], v[98:101], v[158:161], v[62:65]
	v_mfma_f32_16x16x32_bf16 v[58:61], v[122:125], v[158:161], v[58:61]
	v_mfma_f32_16x16x32_bf16 v[46:49], v[98:101], v[170:173], v[46:49]
	v_mfma_f32_16x16x32_bf16 v[42:45], v[122:125], v[170:173], v[42:45]
	v_mfma_f32_16x16x32_bf16 v[30:33], v[98:101], v[178:181], v[30:33]
	v_mfma_f32_16x16x32_bf16 v[26:29], v[122:125], v[178:181], v[26:29]
	v_mfma_f32_16x16x32_bf16 v[14:17], v[98:101], v[186:189], v[14:17]
	v_mfma_f32_16x16x32_bf16 v[10:13], v[122:125], v[186:189], v[10:13]
	v_mfma_f32_16x16x32_bf16 v[62:65], v[110:113], v[166:169], v[62:65]
	v_mfma_f32_16x16x32_bf16 v[58:61], v[130:133], v[166:169], v[58:61]
	v_mfma_f32_16x16x32_bf16 v[46:49], v[110:113], v[174:177], v[46:49]
	v_mfma_f32_16x16x32_bf16 v[42:45], v[130:133], v[174:177], v[42:45]
	v_mfma_f32_16x16x32_bf16 v[30:33], v[110:113], v[182:185], v[30:33]
	v_mfma_f32_16x16x32_bf16 v[26:29], v[130:133], v[182:185], v[26:29]
	v_mfma_f32_16x16x32_bf16 v[14:17], v[110:113], v[190:193], v[14:17]
	v_mfma_f32_16x16x32_bf16 v[10:13], v[130:133], v[190:193], v[10:13]
	v_mfma_f32_16x16x32_bf16 v[54:57], v[138:141], v[158:161], v[54:57]
	v_mfma_f32_16x16x32_bf16 v[50:53], v[146:149], v[158:161], v[50:53]
	v_mfma_f32_16x16x32_bf16 v[38:41], v[138:141], v[170:173], v[38:41]
	v_mfma_f32_16x16x32_bf16 v[34:37], v[146:149], v[170:173], v[34:37]
	v_mfma_f32_16x16x32_bf16 v[22:25], v[138:141], v[178:181], v[22:25]
	v_mfma_f32_16x16x32_bf16 v[18:21], v[146:149], v[178:181], v[18:21]
	v_mfma_f32_16x16x32_bf16 v[6:9], v[138:141], v[186:189], v[6:9]
	v_mfma_f32_16x16x32_bf16 v[2:5], v[146:149], v[186:189], v[2:5]
	v_mfma_f32_16x16x32_bf16 v[54:57], v[142:145], v[166:169], v[54:57]
	v_mfma_f32_16x16x32_bf16 v[50:53], v[150:153], v[166:169], v[50:53]
	v_mfma_f32_16x16x32_bf16 v[38:41], v[142:145], v[174:177], v[38:41]
	v_mfma_f32_16x16x32_bf16 v[34:37], v[150:153], v[174:177], v[34:37]
	v_mfma_f32_16x16x32_bf16 v[22:25], v[142:145], v[182:185], v[22:25]
	v_mfma_f32_16x16x32_bf16 v[18:21], v[150:153], v[182:185], v[18:21]
	v_mfma_f32_16x16x32_bf16 v[6:9], v[142:145], v[190:193], v[6:9]
	v_mfma_f32_16x16x32_bf16 v[2:5], v[150:153], v[190:193], v[2:5]
	s_setprio 0
	s_barrier
	s_add_i32 s47, 0, 0x18000
	v_add_u32_e32 v0, s47, v242
	s_add_i32 s48, 0, 0x1c000
	ds_read_b128 v[98:101], v0
	ds_read_b128 v[110:113], v0 offset:1024
	ds_read_b128 v[122:125], v0 offset:2048
	ds_read_b128 v[130:133], v0 offset:3072
	v_add_u32_e32 v0, s48, v242
	ds_read_b128 v[138:141], v0
	ds_read_b128 v[142:145], v0 offset:1024
	ds_read_b128 v[146:149], v0 offset:2048
	ds_read_b128 v[150:153], v0 offset:3072
	s_add_u32 s18, s24, 0x40000
	s_addc_u32 s19, s25, 0
	s_mov_b32 m0, s29
	v_lshl_add_u64 v[216:217], s[18:19], 0, v[198:199]
	ds_read_b128 v[158:161], v247 offset:32768
	ds_read_b128 v[166:169], v247 offset:33792
	ds_read_b128 v[170:173], v247 offset:34816
	ds_read_b128 v[174:177], v247 offset:35840
	ds_read_b128 v[178:181], v247 offset:36864
	ds_read_b128 v[182:185], v247 offset:37888
	ds_read_b128 v[186:189], v247 offset:38912
	ds_read_b128 v[190:193], v247 offset:39936
	global_load_lds_dwordx4 v[216:217], off
	v_lshl_add_u64 v[216:217], s[18:19], 0, v[196:197]
	s_mov_b32 m0, s30
	s_nop 0
	global_load_lds_dwordx4 v[216:217], off
	s_waitcnt vmcnt(8)
	s_waitcnt lgkmcnt(0)
	s_barrier
	s_setprio 1
	s_waitcnt lgkmcnt(0)
	v_mfma_f32_16x16x32_bf16 v[162:165], v[98:101], v[158:161], v[162:165]
	v_mfma_f32_16x16x32_bf16 v[154:157], v[122:125], v[158:161], v[154:157]
	v_mfma_f32_16x16x32_bf16 v[118:121], v[98:101], v[170:173], v[118:121]
	v_mfma_f32_16x16x32_bf16 v[114:117], v[122:125], v[170:173], v[114:117]
	v_mfma_f32_16x16x32_bf16 v[94:97], v[98:101], v[178:181], v[94:97]
	v_mfma_f32_16x16x32_bf16 v[90:93], v[122:125], v[178:181], v[90:93]
	v_mfma_f32_16x16x32_bf16 v[78:81], v[98:101], v[186:189], v[78:81]
	v_mfma_f32_16x16x32_bf16 v[74:77], v[122:125], v[186:189], v[74:77]
	v_mfma_f32_16x16x32_bf16 v[162:165], v[110:113], v[166:169], v[162:165]
	v_mfma_f32_16x16x32_bf16 v[154:157], v[130:133], v[166:169], v[154:157]
	v_mfma_f32_16x16x32_bf16 v[118:121], v[110:113], v[174:177], v[118:121]
	v_mfma_f32_16x16x32_bf16 v[114:117], v[130:133], v[174:177], v[114:117]
	v_mfma_f32_16x16x32_bf16 v[94:97], v[110:113], v[182:185], v[94:97]
	v_mfma_f32_16x16x32_bf16 v[90:93], v[130:133], v[182:185], v[90:93]
	v_mfma_f32_16x16x32_bf16 v[78:81], v[110:113], v[190:193], v[78:81]
	v_mfma_f32_16x16x32_bf16 v[74:77], v[130:133], v[190:193], v[74:77]
	v_mfma_f32_16x16x32_bf16 v[134:137], v[138:141], v[158:161], v[134:137]
	v_mfma_f32_16x16x32_bf16 v[126:129], v[146:149], v[158:161], v[126:129]
	v_mfma_f32_16x16x32_bf16 v[106:109], v[138:141], v[170:173], v[106:109]
	v_mfma_f32_16x16x32_bf16 v[102:105], v[146:149], v[170:173], v[102:105]
	v_mfma_f32_16x16x32_bf16 v[86:89], v[138:141], v[178:181], v[86:89]
	v_mfma_f32_16x16x32_bf16 v[82:85], v[146:149], v[178:181], v[82:85]
	v_mfma_f32_16x16x32_bf16 v[70:73], v[138:141], v[186:189], v[70:73]
	v_mfma_f32_16x16x32_bf16 v[66:69], v[146:149], v[186:189], v[66:69]
	v_mfma_f32_16x16x32_bf16 v[134:137], v[142:145], v[166:169], v[134:137]
	v_mfma_f32_16x16x32_bf16 v[126:129], v[150:153], v[166:169], v[126:129]
	v_mfma_f32_16x16x32_bf16 v[106:109], v[142:145], v[174:177], v[106:109]
	v_mfma_f32_16x16x32_bf16 v[102:105], v[150:153], v[174:177], v[102:105]
	v_mfma_f32_16x16x32_bf16 v[86:89], v[142:145], v[182:185], v[86:89]
	v_mfma_f32_16x16x32_bf16 v[82:85], v[150:153], v[182:185], v[82:85]
	v_mfma_f32_16x16x32_bf16 v[70:73], v[142:145], v[190:193], v[70:73]
	v_mfma_f32_16x16x32_bf16 v[66:69], v[150:153], v[190:193], v[66:69]
	s_setprio 0
	s_barrier
	s_add_i32 s18, s47, s26
	v_lshl_add_u64 v[208:209], v[208:209], 0, s[0:1]
	s_mov_b32 m0, s18
	ds_read_b128 v[158:161], v247 offset:49152
	ds_read_b128 v[166:169], v247 offset:50176
	ds_read_b128 v[170:173], v247 offset:51200
	ds_read_b128 v[174:177], v247 offset:52224
	ds_read_b128 v[178:181], v247 offset:53248
	ds_read_b128 v[182:185], v247 offset:54272
	ds_read_b128 v[186:189], v247 offset:55296
	ds_read_b128 v[190:193], v247 offset:56320
	global_load_lds_dwordx4 v[208:209], off
	s_add_i32 m0, s18, 0x2000
	s_add_u32 s18, s22, 0x40080
	v_lshl_add_u64 v[208:209], v[210:211], 0, s[0:1]
	s_addc_u32 s19, s23, 0
	s_add_i32 s22, s48, s26
	global_load_lds_dwordx4 v[208:209], off
	v_lshl_add_u64 v[208:209], s[18:19], 0, v[198:199]
	s_mov_b32 m0, s22
	s_nop 0
	global_load_lds_dwordx4 v[208:209], off
	v_lshl_add_u64 v[208:209], s[18:19], 0, v[196:197]
	s_add_i32 m0, s22, 0x2000
	s_nop 0
	global_load_lds_dwordx4 v[208:209], off
	v_lshl_add_u64 v[208:209], v[212:213], 0, s[0:1]
	s_mov_b32 m0, s34
	s_nop 0
	global_load_lds_dwordx4 v[208:209], off
	v_lshl_add_u64 v[208:209], v[214:215], 0, s[0:1]
	s_mov_b32 m0, s35
	s_nop 0
	global_load_lds_dwordx4 v[208:209], off
	s_waitcnt vmcnt(8)
	s_waitcnt lgkmcnt(0)
	s_barrier
	s_setprio 1
	s_waitcnt lgkmcnt(0)
	v_mfma_f32_16x16x32_bf16 v[62:65], v[98:101], v[158:161], v[62:65]
	v_mfma_f32_16x16x32_bf16 v[58:61], v[122:125], v[158:161], v[58:61]
	v_mfma_f32_16x16x32_bf16 v[46:49], v[98:101], v[170:173], v[46:49]
	v_mfma_f32_16x16x32_bf16 v[42:45], v[122:125], v[170:173], v[42:45]
	v_mfma_f32_16x16x32_bf16 v[30:33], v[98:101], v[178:181], v[30:33]
	v_mfma_f32_16x16x32_bf16 v[26:29], v[122:125], v[178:181], v[26:29]
	v_mfma_f32_16x16x32_bf16 v[14:17], v[98:101], v[186:189], v[14:17]
	v_mfma_f32_16x16x32_bf16 v[10:13], v[122:125], v[186:189], v[10:13]
	v_mfma_f32_16x16x32_bf16 v[62:65], v[110:113], v[166:169], v[62:65]
	v_mfma_f32_16x16x32_bf16 v[58:61], v[130:133], v[166:169], v[58:61]
	v_mfma_f32_16x16x32_bf16 v[46:49], v[110:113], v[174:177], v[46:49]
	v_mfma_f32_16x16x32_bf16 v[42:45], v[130:133], v[174:177], v[42:45]
	v_mfma_f32_16x16x32_bf16 v[30:33], v[110:113], v[182:185], v[30:33]
	v_mfma_f32_16x16x32_bf16 v[26:29], v[130:133], v[182:185], v[26:29]
	v_mfma_f32_16x16x32_bf16 v[14:17], v[110:113], v[190:193], v[14:17]
	v_mfma_f32_16x16x32_bf16 v[10:13], v[130:133], v[190:193], v[10:13]
	v_mfma_f32_16x16x32_bf16 v[54:57], v[138:141], v[158:161], v[54:57]
	v_mfma_f32_16x16x32_bf16 v[50:53], v[146:149], v[158:161], v[50:53]
	v_mfma_f32_16x16x32_bf16 v[38:41], v[138:141], v[170:173], v[38:41]
	v_mfma_f32_16x16x32_bf16 v[34:37], v[146:149], v[170:173], v[34:37]
	v_mfma_f32_16x16x32_bf16 v[22:25], v[138:141], v[178:181], v[22:25]
	v_mfma_f32_16x16x32_bf16 v[18:21], v[146:149], v[178:181], v[18:21]
	v_mfma_f32_16x16x32_bf16 v[6:9], v[138:141], v[186:189], v[6:9]
	v_mfma_f32_16x16x32_bf16 v[2:5], v[146:149], v[186:189], v[2:5]
	v_mfma_f32_16x16x32_bf16 v[54:57], v[142:145], v[166:169], v[54:57]
	v_mfma_f32_16x16x32_bf16 v[50:53], v[150:153], v[166:169], v[50:53]
	v_mfma_f32_16x16x32_bf16 v[38:41], v[142:145], v[174:177], v[38:41]
	v_mfma_f32_16x16x32_bf16 v[34:37], v[150:153], v[174:177], v[34:37]
	v_mfma_f32_16x16x32_bf16 v[22:25], v[142:145], v[182:185], v[22:25]
	v_mfma_f32_16x16x32_bf16 v[18:21], v[150:153], v[182:185], v[18:21]
	v_mfma_f32_16x16x32_bf16 v[6:9], v[142:145], v[190:193], v[6:9]
	v_mfma_f32_16x16x32_bf16 v[2:5], v[150:153], v[190:193], v[2:5]
	s_setprio 0
	s_barrier
	s_add_i32 s46, s46, 2
	s_add_u32 s44, s44, 0x100
	s_addc_u32 s45, s45, 0
	s_cmp_gt_u32 s46, 13
	s_mov_b64 s[18:19], s[20:21]
	s_cbranch_scc0 .LBB0_106
	s_and_b64 vcc, exec, s[10:11]
	s_cbranch_vccz .LBB0_109
	s_barrier

.LBB0_611:
	s_add_u32 s22, s45, s20
	s_addc_u32 s23, s46, s21
	s_add_u32 s22, s22, 0x5000100
	s_addc_u32 s23, s23, 0
	s_add_u32 s50, s47, s20
	s_addc_u32 s51, s48, s21
	s_add_i32 s52, 0, 0x10000
	s_cmpk_eq_i32 s20, 0x700
	s_cselect_b32 s25, s42, s23
	s_cselect_b32 s24, s19, s22
	s_cselect_b32 s23, s44, s51
	s_cselect_b32 s22, s43, s50
	s_add_i32 s53, 0, 0x14000
	v_add_u32_e32 v160, s52, v144
	v_add_u32_e32 v176, s53, v144
	ds_read_b128 v[148:151], v160
	ds_read_b128 v[152:155], v160 offset:1024
	ds_read_b128 v[156:159], v160 offset:2048
	ds_read_b128 v[160:163], v160 offset:3072
	ds_read_b128 v[164:167], v176
	ds_read_b128 v[168:171], v176 offset:1024
	ds_read_b128 v[172:175], v176 offset:2048
	ds_read_b128 v[176:179], v176 offset:3072
	v_lshl_add_u64 v[192:193], v[138:139], 0, s[20:21]
	s_add_i32 m0, s27, 0xc000
	ds_read_b128 v[180:183], v147
	ds_read_b128 v[184:187], v147 offset:1024
	ds_read_b128 v[188:191], v147 offset:2048
	ds_read_b128 v[196:199], v147 offset:3072
	ds_read_b128 v[202:205], v147 offset:4096
	ds_read_b128 v[206:209], v147 offset:5120
	ds_read_b128 v[210:213], v147 offset:6144
	ds_read_b128 v[214:217], v147 offset:7168
	global_load_lds_dwordx4 v[192:193], off
	v_lshl_add_u64 v[192:193], v[140:141], 0, s[20:21]
	s_add_i32 m0, s27, 0xe000
	s_nop 0
	global_load_lds_dwordx4 v[192:193], off
	s_waitcnt vmcnt(8)
	s_waitcnt lgkmcnt(0)
	s_barrier
	s_setprio 1
	s_waitcnt lgkmcnt(0)
	v_mfma_f32_16x16x32_bf16 v[126:129], v[148:151], v[180:183], v[126:129]
	v_mfma_f32_16x16x32_bf16 v[122:125], v[156:159], v[180:183], v[122:125]
	v_mfma_f32_16x16x32_bf16 v[114:117], v[148:151], v[188:191], v[114:117]
	v_mfma_f32_16x16x32_bf16 v[106:109], v[156:159], v[188:191], v[106:109]
	v_mfma_f32_16x16x32_bf16 v[98:101], v[148:151], v[202:205], v[98:101]
	v_mfma_f32_16x16x32_bf16 v[90:93], v[156:159], v[202:205], v[90:93]
	v_mfma_f32_16x16x32_bf16 v[82:85], v[148:151], v[210:213], v[82:85]
	v_mfma_f32_16x16x32_bf16 v[74:77], v[156:159], v[210:213], v[74:77]
	v_mfma_f32_16x16x32_bf16 v[126:129], v[152:155], v[184:187], v[126:129]
	v_mfma_f32_16x16x32_bf16 v[122:125], v[160:163], v[184:187], v[122:125]
	v_mfma_f32_16x16x32_bf16 v[114:117], v[152:155], v[196:199], v[114:117]
	v_mfma_f32_16x16x32_bf16 v[106:109], v[160:163], v[196:199], v[106:109]
	v_mfma_f32_16x16x32_bf16 v[98:101], v[152:155], v[206:209], v[98:101]
	v_mfma_f32_16x16x32_bf16 v[90:93], v[160:163], v[206:209], v[90:93]
	v_mfma_f32_16x16x32_bf16 v[82:85], v[152:155], v[214:217], v[82:85]
	v_mfma_f32_16x16x32_bf16 v[74:77], v[160:163], v[214:217], v[74:77]
	v_mfma_f32_16x16x32_bf16 v[118:121], v[164:167], v[180:183], v[118:121]
	v_mfma_f32_16x16x32_bf16 v[110:113], v[172:175], v[180:183], v[110:113]
	v_mfma_f32_16x16x32_bf16 v[102:105], v[164:167], v[188:191], v[102:105]
	v_mfma_f32_16x16x32_bf16 v[94:97], v[172:175], v[188:191], v[94:97]
	v_mfma_f32_16x16x32_bf16 v[86:89], v[164:167], v[202:205], v[86:89]
	v_mfma_f32_16x16x32_bf16 v[78:81], v[172:175], v[202:205], v[78:81]
	v_mfma_f32_16x16x32_bf16 v[70:73], v[164:167], v[210:213], v[70:73]
	v_mfma_f32_16x16x32_bf16 v[66:69], v[172:175], v[210:213], v[66:69]
	v_mfma_f32_16x16x32_bf16 v[118:121], v[168:171], v[184:187], v[118:121]
	v_mfma_f32_16x16x32_bf16 v[110:113], v[176:179], v[184:187], v[110:113]
	v_mfma_f32_16x16x32_bf16 v[102:105], v[168:171], v[196:199], v[102:105]
	v_mfma_f32_16x16x32_bf16 v[94:97], v[176:179], v[196:199], v[94:97]
	v_mfma_f32_16x16x32_bf16 v[86:89], v[168:171], v[206:209], v[86:89]
	v_mfma_f32_16x16x32_bf16 v[78:81], v[176:179], v[206:209], v[78:81]
	v_mfma_f32_16x16x32_bf16 v[70:73], v[168:171], v[214:217], v[70:73]
	v_mfma_f32_16x16x32_bf16 v[66:69], v[176:179], v[214:217], v[66:69]
	s_setprio 0
	s_barrier
	s_add_i32 s50, s52, s26
	v_lshl_add_u64 v[192:193], s[22:23], 0, v[130:131]
	s_mov_b32 m0, s50
	ds_read_b128 v[180:183], v147 offset:16384
	ds_read_b128 v[184:187], v147 offset:17408
	ds_read_b128 v[188:191], v147 offset:18432
	ds_read_b128 v[196:199], v147 offset:19456
	ds_read_b128 v[202:205], v147 offset:20480
	ds_read_b128 v[206:209], v147 offset:21504
	ds_read_b128 v[210:213], v147 offset:22528
	ds_read_b128 v[214:217], v147 offset:23552
	global_load_lds_dwordx4 v[192:193], off
	s_add_i32 m0, s50, 0x2000
	s_add_u32 s50, s22, 0x40000
	v_lshl_add_u64 v[218:219], s[22:23], 0, v[132:133]
	s_addc_u32 s51, s23, 0
	s_add_i32 s52, s53, s26
	global_load_lds_dwordx4 v[218:219], off
	v_lshl_add_u64 v[220:221], s[50:51], 0, v[130:131]
	s_mov_b32 m0, s52
	v_lshl_add_u64 v[222:223], s[24:25], 0, v[132:133]
	global_load_lds_dwordx4 v[220:221], off
	v_lshl_add_u64 v[220:221], s[50:51], 0, v[132:133]
	s_add_i32 m0, s52, 0x2000
	s_nop 0
	global_load_lds_dwordx4 v[220:221], off
	v_lshl_add_u64 v[220:221], s[24:25], 0, v[130:131]
	s_mov_b32 m0, s27
	s_nop 0
	global_load_lds_dwordx4 v[220:221], off
	s_mov_b32 m0, s28
	s_nop 0
	global_load_lds_dwordx4 v[222:223], off
	s_waitcnt vmcnt(8)
	s_waitcnt lgkmcnt(0)
	s_barrier
	s_setprio 1
	s_waitcnt lgkmcnt(0)
	v_mfma_f32_16x16x32_bf16 v[62:65], v[148:151], v[180:183], v[62:65]
	v_mfma_f32_16x16x32_bf16 v[58:61], v[156:159], v[180:183], v[58:61]
	v_mfma_f32_16x16x32_bf16 v[50:53], v[148:151], v[188:191], v[50:53]
	v_mfma_f32_16x16x32_bf16 v[42:45], v[156:159], v[188:191], v[42:45]
	v_mfma_f32_16x16x32_bf16 v[34:37], v[148:151], v[202:205], v[34:37]
	v_mfma_f32_16x16x32_bf16 v[26:29], v[156:159], v[202:205], v[26:29]
	v_mfma_f32_16x16x32_bf16 v[18:21], v[148:151], v[210:213], v[18:21]
	v_mfma_f32_16x16x32_bf16 v[10:13], v[156:159], v[210:213], v[10:13]
	v_mfma_f32_16x16x32_bf16 v[62:65], v[152:155], v[184:187], v[62:65]
	v_mfma_f32_16x16x32_bf16 v[58:61], v[160:163], v[184:187], v[58:61]
	v_mfma_f32_16x16x32_bf16 v[50:53], v[152:155], v[196:199], v[50:53]
	v_mfma_f32_16x16x32_bf16 v[42:45], v[160:163], v[196:199], v[42:45]
	v_mfma_f32_16x16x32_bf16 v[34:37], v[152:155], v[206:209], v[34:37]
	v_mfma_f32_16x16x32_bf16 v[26:29], v[160:163], v[206:209], v[26:29]
	v_mfma_f32_16x16x32_bf16 v[18:21], v[152:155], v[214:217], v[18:21]
	v_mfma_f32_16x16x32_bf16 v[10:13], v[160:163], v[214:217], v[10:13]
	v_mfma_f32_16x16x32_bf16 v[54:57], v[164:167], v[180:183], v[54:57]
	v_mfma_f32_16x16x32_bf16 v[46:49], v[172:175], v[180:183], v[46:49]
	v_mfma_f32_16x16x32_bf16 v[38:41], v[164:167], v[188:191], v[38:41]
	v_mfma_f32_16x16x32_bf16 v[30:33], v[172:175], v[188:191], v[30:33]
	v_mfma_f32_16x16x32_bf16 v[22:25], v[164:167], v[202:205], v[22:25]
	v_mfma_f32_16x16x32_bf16 v[14:17], v[172:175], v[202:205], v[14:17]
	v_mfma_f32_16x16x32_bf16 v[6:9], v[164:167], v[210:213], v[6:9]
	v_mfma_f32_16x16x32_bf16 v[2:5], v[172:175], v[210:213], v[2:5]
	v_mfma_f32_16x16x32_bf16 v[54:57], v[168:171], v[184:187], v[54:57]
	v_mfma_f32_16x16x32_bf16 v[46:49], v[176:179], v[184:187], v[46:49]
	v_mfma_f32_16x16x32_bf16 v[38:41], v[168:171], v[196:199], v[38:41]
	v_mfma_f32_16x16x32_bf16 v[30:33], v[176:179], v[196:199], v[30:33]
	v_mfma_f32_16x16x32_bf16 v[22:25], v[168:171], v[206:209], v[22:25]
	v_mfma_f32_16x16x32_bf16 v[14:17], v[176:179], v[206:209], v[14:17]
	v_mfma_f32_16x16x32_bf16 v[6:9], v[168:171], v[214:217], v[6:9]
	v_mfma_f32_16x16x32_bf16 v[2:5], v[176:179], v[214:217], v[2:5]
	s_setprio 0
	s_barrier
	s_add_i32 s50, 0, 0x18000
	s_add_i32 s51, 0, 0x1c000
	v_add_u32_e32 v160, s50, v144
	v_add_u32_e32 v176, s51, v144
	ds_read_b128 v[148:151], v160
	ds_read_b128 v[152:155], v160 offset:1024
	ds_read_b128 v[156:159], v160 offset:2048
	ds_read_b128 v[160:163], v160 offset:3072
	ds_read_b128 v[164:167], v176
	ds_read_b128 v[168:171], v176 offset:1024
	ds_read_b128 v[172:175], v176 offset:2048
	ds_read_b128 v[176:179], v176 offset:3072
	s_add_u32 s24, s24, 0x40000
	s_addc_u32 s25, s25, 0
	s_mov_b32 m0, s29
	v_lshl_add_u64 v[224:225], s[24:25], 0, v[130:131]
	ds_read_b128 v[180:183], v147 offset:32768
	ds_read_b128 v[184:187], v147 offset:33792
	ds_read_b128 v[188:191], v147 offset:34816
	ds_read_b128 v[196:199], v147 offset:35840
	ds_read_b128 v[202:205], v147 offset:36864
	ds_read_b128 v[206:209], v147 offset:37888
	ds_read_b128 v[210:213], v147 offset:38912
	ds_read_b128 v[214:217], v147 offset:39936
	global_load_lds_dwordx4 v[224:225], off
	v_lshl_add_u64 v[224:225], s[24:25], 0, v[132:133]
	s_mov_b32 m0, s30
	s_nop 0
	global_load_lds_dwordx4 v[224:225], off
	s_waitcnt vmcnt(8)
	s_waitcnt lgkmcnt(0)
	s_barrier
	s_setprio 1
	s_waitcnt lgkmcnt(0)
	v_mfma_f32_16x16x32_bf16 v[126:129], v[148:151], v[180:183], v[126:129]
	v_mfma_f32_16x16x32_bf16 v[122:125], v[156:159], v[180:183], v[122:125]
	v_mfma_f32_16x16x32_bf16 v[114:117], v[148:151], v[188:191], v[114:117]
	v_mfma_f32_16x16x32_bf16 v[106:109], v[156:159], v[188:191], v[106:109]
	v_mfma_f32_16x16x32_bf16 v[98:101], v[148:151], v[202:205], v[98:101]
	v_mfma_f32_16x16x32_bf16 v[90:93], v[156:159], v[202:205], v[90:93]
	v_mfma_f32_16x16x32_bf16 v[82:85], v[148:151], v[210:213], v[82:85]
	v_mfma_f32_16x16x32_bf16 v[74:77], v[156:159], v[210:213], v[74:77]
	v_mfma_f32_16x16x32_bf16 v[126:129], v[152:155], v[184:187], v[126:129]
	v_mfma_f32_16x16x32_bf16 v[122:125], v[160:163], v[184:187], v[122:125]
	v_mfma_f32_16x16x32_bf16 v[114:117], v[152:155], v[196:199], v[114:117]
	v_mfma_f32_16x16x32_bf16 v[106:109], v[160:163], v[196:199], v[106:109]
	v_mfma_f32_16x16x32_bf16 v[98:101], v[152:155], v[206:209], v[98:101]
	v_mfma_f32_16x16x32_bf16 v[90:93], v[160:163], v[206:209], v[90:93]
	v_mfma_f32_16x16x32_bf16 v[82:85], v[152:155], v[214:217], v[82:85]
	v_mfma_f32_16x16x32_bf16 v[74:77], v[160:163], v[214:217], v[74:77]
	v_mfma_f32_16x16x32_bf16 v[118:121], v[164:167], v[180:183], v[118:121]
	v_mfma_f32_16x16x32_bf16 v[110:113], v[172:175], v[180:183], v[110:113]
	v_mfma_f32_16x16x32_bf16 v[102:105], v[164:167], v[188:191], v[102:105]
	v_mfma_f32_16x16x32_bf16 v[94:97], v[172:175], v[188:191], v[94:97]
	v_mfma_f32_16x16x32_bf16 v[86:89], v[164:167], v[202:205], v[86:89]
	v_mfma_f32_16x16x32_bf16 v[78:81], v[172:175], v[202:205], v[78:81]
	v_mfma_f32_16x16x32_bf16 v[70:73], v[164:167], v[210:213], v[70:73]
	v_mfma_f32_16x16x32_bf16 v[66:69], v[172:175], v[210:213], v[66:69]
	v_mfma_f32_16x16x32_bf16 v[118:121], v[168:171], v[184:187], v[118:121]
	v_mfma_f32_16x16x32_bf16 v[110:113], v[176:179], v[184:187], v[110:113]
	v_mfma_f32_16x16x32_bf16 v[102:105], v[168:171], v[196:199], v[102:105]
	v_mfma_f32_16x16x32_bf16 v[94:97], v[176:179], v[196:199], v[94:97]
	v_mfma_f32_16x16x32_bf16 v[86:89], v[168:171], v[206:209], v[86:89]
	v_mfma_f32_16x16x32_bf16 v[78:81], v[176:179], v[206:209], v[78:81]
	v_mfma_f32_16x16x32_bf16 v[70:73], v[168:171], v[214:217], v[70:73]
	v_mfma_f32_16x16x32_bf16 v[66:69], v[176:179], v[214:217], v[66:69]
	s_setprio 0
	s_barrier
	s_add_i32 s24, s50, s26
	v_lshl_add_u64 v[192:193], v[192:193], 0, s[0:1]
	s_mov_b32 m0, s24
	ds_read_b128 v[180:183], v147 offset:49152
	ds_read_b128 v[184:187], v147 offset:50176
	ds_read_b128 v[188:191], v147 offset:51200
	ds_read_b128 v[196:199], v147 offset:52224
	ds_read_b128 v[202:205], v147 offset:53248
	ds_read_b128 v[206:209], v147 offset:54272
	ds_read_b128 v[210:213], v147 offset:55296
	ds_read_b128 v[214:217], v147 offset:56320
	global_load_lds_dwordx4 v[192:193], off
	s_add_i32 m0, s24, 0x2000
	s_add_u32 s22, s22, 0x40080
	v_lshl_add_u64 v[192:193], v[218:219], 0, s[0:1]
	s_addc_u32 s23, s23, 0
	s_add_i32 s24, s51, s26
	global_load_lds_dwordx4 v[192:193], off
	v_lshl_add_u64 v[192:193], s[22:23], 0, v[130:131]
	s_mov_b32 m0, s24
	s_nop 0
	global_load_lds_dwordx4 v[192:193], off
	v_lshl_add_u64 v[192:193], s[22:23], 0, v[132:133]
	s_add_i32 m0, s24, 0x2000
	s_nop 0
	global_load_lds_dwordx4 v[192:193], off
	v_lshl_add_u64 v[192:193], v[220:221], 0, s[0:1]
	s_mov_b32 m0, s31
	s_nop 0
	global_load_lds_dwordx4 v[192:193], off
	v_lshl_add_u64 v[192:193], v[222:223], 0, s[0:1]
	s_mov_b32 m0, s33
	s_nop 0
	global_load_lds_dwordx4 v[192:193], off
	s_waitcnt vmcnt(8)
	s_waitcnt lgkmcnt(0)
	s_barrier
	s_setprio 1
	s_waitcnt lgkmcnt(0)
	v_mfma_f32_16x16x32_bf16 v[62:65], v[148:151], v[180:183], v[62:65]
	v_mfma_f32_16x16x32_bf16 v[58:61], v[156:159], v[180:183], v[58:61]
	v_mfma_f32_16x16x32_bf16 v[50:53], v[148:151], v[188:191], v[50:53]
	v_mfma_f32_16x16x32_bf16 v[42:45], v[156:159], v[188:191], v[42:45]
	v_mfma_f32_16x16x32_bf16 v[34:37], v[148:151], v[202:205], v[34:37]
	v_mfma_f32_16x16x32_bf16 v[26:29], v[156:159], v[202:205], v[26:29]
	v_mfma_f32_16x16x32_bf16 v[18:21], v[148:151], v[210:213], v[18:21]
	v_mfma_f32_16x16x32_bf16 v[10:13], v[156:159], v[210:213], v[10:13]
	v_mfma_f32_16x16x32_bf16 v[62:65], v[152:155], v[184:187], v[62:65]
	v_mfma_f32_16x16x32_bf16 v[58:61], v[160:163], v[184:187], v[58:61]
	v_mfma_f32_16x16x32_bf16 v[50:53], v[152:155], v[196:199], v[50:53]
	v_mfma_f32_16x16x32_bf16 v[42:45], v[160:163], v[196:199], v[42:45]
	v_mfma_f32_16x16x32_bf16 v[34:37], v[152:155], v[206:209], v[34:37]
	v_mfma_f32_16x16x32_bf16 v[26:29], v[160:163], v[206:209], v[26:29]
	v_mfma_f32_16x16x32_bf16 v[18:21], v[152:155], v[214:217], v[18:21]
	v_mfma_f32_16x16x32_bf16 v[10:13], v[160:163], v[214:217], v[10:13]
	v_mfma_f32_16x16x32_bf16 v[54:57], v[164:167], v[180:183], v[54:57]
	v_mfma_f32_16x16x32_bf16 v[46:49], v[172:175], v[180:183], v[46:49]
	v_mfma_f32_16x16x32_bf16 v[38:41], v[164:167], v[188:191], v[38:41]
	v_mfma_f32_16x16x32_bf16 v[30:33], v[172:175], v[188:191], v[30:33]
	v_mfma_f32_16x16x32_bf16 v[22:25], v[164:167], v[202:205], v[22:25]
	v_mfma_f32_16x16x32_bf16 v[14:17], v[172:175], v[202:205], v[14:17]
	v_mfma_f32_16x16x32_bf16 v[6:9], v[164:167], v[210:213], v[6:9]
	v_mfma_f32_16x16x32_bf16 v[2:5], v[172:175], v[210:213], v[2:5]
	v_mfma_f32_16x16x32_bf16 v[54:57], v[168:171], v[184:187], v[54:57]
	v_mfma_f32_16x16x32_bf16 v[46:49], v[176:179], v[184:187], v[46:49]
	v_mfma_f32_16x16x32_bf16 v[38:41], v[168:171], v[196:199], v[38:41]
	v_mfma_f32_16x16x32_bf16 v[30:33], v[176:179], v[196:199], v[30:33]
	v_mfma_f32_16x16x32_bf16 v[22:25], v[168:171], v[206:209], v[22:25]
	v_mfma_f32_16x16x32_bf16 v[14:17], v[176:179], v[206:209], v[14:17]
	v_mfma_f32_16x16x32_bf16 v[6:9], v[168:171], v[214:217], v[6:9]
	v_mfma_f32_16x16x32_bf16 v[2:5], v[176:179], v[214:217], v[2:5]
	s_setprio 0
	s_barrier
	s_add_i32 s49, s49, 2
	s_add_u32 s20, s20, 0x100
	s_addc_u32 s21, s21, 0
	s_cmp_gt_u32 s49, 13
	s_cbranch_scc0 .LBB0_611
	s_and_b64 vcc, exec, s[10:11]
	s_cbranch_vccz .LBB0_614
	s_barrier

.LBB0_636:
	s_add_u32 s20, s18, 0x100
	s_addc_u32 s21, s19, 0
	s_add_i32 s47, 0, 0x10000
	s_cmp_eq_u32 s46, 40
	s_cselect_b32 s25, s15, s21
	s_cselect_b32 s24, s14, s20
	v_add_u32_e32 v0, s47, v242
	s_cselect_b32 s23, s43, s45
	s_cselect_b32 s22, s42, s44
	s_add_i32 s48, 0, 0x14000
	ds_read_b128 v[90:93], v0
	ds_read_b128 v[102:105], v0 offset:1024
	ds_read_b128 v[114:117], v0 offset:2048
	ds_read_b128 v[122:125], v0 offset:3072
	v_add_u32_e32 v0, s48, v242
	ds_read_b128 v[130:133], v0
	ds_read_b128 v[142:145], v0 offset:1024
	ds_read_b128 v[146:149], v0 offset:2048
	ds_read_b128 v[150:153], v0 offset:3072
	v_lshl_add_u64 v[208:209], s[18:19], 0, v[204:205]
	s_add_i32 m0, s27, 0xc000
	ds_read_b128 v[154:157], v247
	ds_read_b128 v[162:165], v247 offset:1024
	ds_read_b128 v[170:173], v247 offset:2048
	ds_read_b128 v[174:177], v247 offset:3072
	ds_read_b128 v[178:181], v247 offset:4096
	ds_read_b128 v[182:185], v247 offset:5120
	ds_read_b128 v[186:189], v247 offset:6144
	ds_read_b128 v[190:193], v247 offset:7168
	global_load_lds_dwordx4 v[208:209], off
	v_lshl_add_u64 v[208:209], s[18:19], 0, v[206:207]
	s_add_i32 m0, s27, 0xe000
	s_nop 0
	global_load_lds_dwordx4 v[208:209], off
	s_waitcnt vmcnt(8)
	s_waitcnt lgkmcnt(0)
	s_barrier
	s_setprio 1
	s_waitcnt lgkmcnt(0)
	v_mfma_f32_16x16x32_bf16 v[166:169], v[90:93], v[154:157], v[166:169]
	v_mfma_f32_16x16x32_bf16 v[158:161], v[114:117], v[154:157], v[158:161]
	v_mfma_f32_16x16x32_bf16 v[126:129], v[90:93], v[170:173], v[126:129]
	v_mfma_f32_16x16x32_bf16 v[118:121], v[114:117], v[170:173], v[118:121]
	v_mfma_f32_16x16x32_bf16 v[98:101], v[90:93], v[178:181], v[98:101]
	v_mfma_f32_16x16x32_bf16 v[94:97], v[114:117], v[178:181], v[94:97]
	v_mfma_f32_16x16x32_bf16 v[78:81], v[90:93], v[186:189], v[78:81]
	v_mfma_f32_16x16x32_bf16 v[74:77], v[114:117], v[186:189], v[74:77]
	v_mfma_f32_16x16x32_bf16 v[166:169], v[102:105], v[162:165], v[166:169]
	v_mfma_f32_16x16x32_bf16 v[158:161], v[122:125], v[162:165], v[158:161]
	v_mfma_f32_16x16x32_bf16 v[126:129], v[102:105], v[174:177], v[126:129]
	v_mfma_f32_16x16x32_bf16 v[118:121], v[122:125], v[174:177], v[118:121]
	v_mfma_f32_16x16x32_bf16 v[98:101], v[102:105], v[182:185], v[98:101]
	v_mfma_f32_16x16x32_bf16 v[94:97], v[122:125], v[182:185], v[94:97]
	v_mfma_f32_16x16x32_bf16 v[78:81], v[102:105], v[190:193], v[78:81]
	v_mfma_f32_16x16x32_bf16 v[74:77], v[122:125], v[190:193], v[74:77]
	v_mfma_f32_16x16x32_bf16 v[138:141], v[130:133], v[154:157], v[138:141]
	v_mfma_f32_16x16x32_bf16 v[134:137], v[146:149], v[154:157], v[134:137]
	v_mfma_f32_16x16x32_bf16 v[110:113], v[130:133], v[170:173], v[110:113]
	v_mfma_f32_16x16x32_bf16 v[106:109], v[146:149], v[170:173], v[106:109]
	v_mfma_f32_16x16x32_bf16 v[86:89], v[130:133], v[178:181], v[86:89]
	v_mfma_f32_16x16x32_bf16 v[82:85], v[146:149], v[178:181], v[82:85]
	v_mfma_f32_16x16x32_bf16 v[70:73], v[130:133], v[186:189], v[70:73]
	v_mfma_f32_16x16x32_bf16 v[66:69], v[146:149], v[186:189], v[66:69]
	v_mfma_f32_16x16x32_bf16 v[138:141], v[142:145], v[162:165], v[138:141]
	v_mfma_f32_16x16x32_bf16 v[134:137], v[150:153], v[162:165], v[134:137]
	v_mfma_f32_16x16x32_bf16 v[110:113], v[142:145], v[174:177], v[110:113]
	v_mfma_f32_16x16x32_bf16 v[106:109], v[150:153], v[174:177], v[106:109]
	v_mfma_f32_16x16x32_bf16 v[86:89], v[142:145], v[182:185], v[86:89]
	v_mfma_f32_16x16x32_bf16 v[82:85], v[150:153], v[182:185], v[82:85]
	v_mfma_f32_16x16x32_bf16 v[70:73], v[142:145], v[190:193], v[70:73]
	v_mfma_f32_16x16x32_bf16 v[66:69], v[150:153], v[190:193], v[66:69]
	s_setprio 0
	s_barrier
	s_add_i32 s18, s47, s26
	v_lshl_add_u64 v[208:209], s[22:23], 0, v[198:199]
	s_mov_b32 m0, s18
	ds_read_b128 v[154:157], v247 offset:16384
	ds_read_b128 v[162:165], v247 offset:17408
	ds_read_b128 v[170:173], v247 offset:18432
	ds_read_b128 v[174:177], v247 offset:19456
	ds_read_b128 v[178:181], v247 offset:20480
	ds_read_b128 v[182:185], v247 offset:21504
	ds_read_b128 v[186:189], v247 offset:22528
	ds_read_b128 v[190:193], v247 offset:23552
	global_load_lds_dwordx4 v[208:209], off
	s_add_i32 m0, s18, 0x2000
	s_add_u32 s18, s22, 0xb0000
	v_lshl_add_u64 v[210:211], s[22:23], 0, v[196:197]
	s_addc_u32 s19, s23, 0
	s_add_i32 s47, s48, s26
	global_load_lds_dwordx4 v[210:211], off
	v_lshl_add_u64 v[212:213], s[18:19], 0, v[198:199]
	s_mov_b32 m0, s47
	v_lshl_add_u64 v[214:215], s[24:25], 0, v[196:197]
	global_load_lds_dwordx4 v[212:213], off
	v_lshl_add_u64 v[212:213], s[18:19], 0, v[196:197]
	s_add_i32 m0, s47, 0x2000
	s_nop 0
	global_load_lds_dwordx4 v[212:213], off
	v_lshl_add_u64 v[212:213], s[24:25], 0, v[198:199]
	s_mov_b32 m0, s27
	s_nop 0
	global_load_lds_dwordx4 v[212:213], off
	s_mov_b32 m0, s28
	s_nop 0
	global_load_lds_dwordx4 v[214:215], off
	s_waitcnt vmcnt(8)
	s_waitcnt lgkmcnt(0)
	s_barrier
	s_setprio 1
	s_waitcnt lgkmcnt(0)
	v_mfma_f32_16x16x32_bf16 v[62:65], v[90:93], v[154:157], v[62:65]
	v_mfma_f32_16x16x32_bf16 v[58:61], v[114:117], v[154:157], v[58:61]
	v_mfma_f32_16x16x32_bf16 v[46:49], v[90:93], v[170:173], v[46:49]
	v_mfma_f32_16x16x32_bf16 v[42:45], v[114:117], v[170:173], v[42:45]
	v_mfma_f32_16x16x32_bf16 v[30:33], v[90:93], v[178:181], v[30:33]
	v_mfma_f32_16x16x32_bf16 v[26:29], v[114:117], v[178:181], v[26:29]
	v_mfma_f32_16x16x32_bf16 v[14:17], v[90:93], v[186:189], v[14:17]
	v_mfma_f32_16x16x32_bf16 v[10:13], v[114:117], v[186:189], v[10:13]
	v_mfma_f32_16x16x32_bf16 v[62:65], v[102:105], v[162:165], v[62:65]
	v_mfma_f32_16x16x32_bf16 v[58:61], v[122:125], v[162:165], v[58:61]
	v_mfma_f32_16x16x32_bf16 v[46:49], v[102:105], v[174:177], v[46:49]
	v_mfma_f32_16x16x32_bf16 v[42:45], v[122:125], v[174:177], v[42:45]
	v_mfma_f32_16x16x32_bf16 v[30:33], v[102:105], v[182:185], v[30:33]
	v_mfma_f32_16x16x32_bf16 v[26:29], v[122:125], v[182:185], v[26:29]
	v_mfma_f32_16x16x32_bf16 v[14:17], v[102:105], v[190:193], v[14:17]
	v_mfma_f32_16x16x32_bf16 v[10:13], v[122:125], v[190:193], v[10:13]
	v_mfma_f32_16x16x32_bf16 v[54:57], v[130:133], v[154:157], v[54:57]
	v_mfma_f32_16x16x32_bf16 v[50:53], v[146:149], v[154:157], v[50:53]
	v_mfma_f32_16x16x32_bf16 v[38:41], v[130:133], v[170:173], v[38:41]
	v_mfma_f32_16x16x32_bf16 v[34:37], v[146:149], v[170:173], v[34:37]
	v_mfma_f32_16x16x32_bf16 v[22:25], v[130:133], v[178:181], v[22:25]
	v_mfma_f32_16x16x32_bf16 v[18:21], v[146:149], v[178:181], v[18:21]
	v_mfma_f32_16x16x32_bf16 v[6:9], v[130:133], v[186:189], v[6:9]
	v_mfma_f32_16x16x32_bf16 v[2:5], v[146:149], v[186:189], v[2:5]
	v_mfma_f32_16x16x32_bf16 v[54:57], v[142:145], v[162:165], v[54:57]
	v_mfma_f32_16x16x32_bf16 v[50:53], v[150:153], v[162:165], v[50:53]
	v_mfma_f32_16x16x32_bf16 v[38:41], v[142:145], v[174:177], v[38:41]
	v_mfma_f32_16x16x32_bf16 v[34:37], v[150:153], v[174:177], v[34:37]
	v_mfma_f32_16x16x32_bf16 v[22:25], v[142:145], v[182:185], v[22:25]
	v_mfma_f32_16x16x32_bf16 v[18:21], v[150:153], v[182:185], v[18:21]
	v_mfma_f32_16x16x32_bf16 v[6:9], v[142:145], v[190:193], v[6:9]
	v_mfma_f32_16x16x32_bf16 v[2:5], v[150:153], v[190:193], v[2:5]
	s_setprio 0
	s_barrier
	s_add_i32 s47, 0, 0x18000
	v_add_u32_e32 v0, s47, v242
	s_add_i32 s48, 0, 0x1c000
	ds_read_b128 v[90:93], v0
	ds_read_b128 v[102:105], v0 offset:1024
	ds_read_b128 v[114:117], v0 offset:2048
	ds_read_b128 v[122:125], v0 offset:3072
	v_add_u32_e32 v0, s48, v242
	ds_read_b128 v[130:133], v0
	ds_read_b128 v[142:145], v0 offset:1024
	ds_read_b128 v[146:149], v0 offset:2048
	ds_read_b128 v[150:153], v0 offset:3072
	s_add_u32 s18, s24, 0xb0000
	s_addc_u32 s19, s25, 0
	s_mov_b32 m0, s29
	v_lshl_add_u64 v[216:217], s[18:19], 0, v[198:199]
	ds_read_b128 v[154:157], v247 offset:32768
	ds_read_b128 v[162:165], v247 offset:33792
	ds_read_b128 v[170:173], v247 offset:34816
	ds_read_b128 v[174:177], v247 offset:35840
	ds_read_b128 v[178:181], v247 offset:36864
	ds_read_b128 v[182:185], v247 offset:37888
	ds_read_b128 v[186:189], v247 offset:38912
	ds_read_b128 v[190:193], v247 offset:39936
	global_load_lds_dwordx4 v[216:217], off
	v_lshl_add_u64 v[216:217], s[18:19], 0, v[196:197]
	s_mov_b32 m0, s30
	s_nop 0
	global_load_lds_dwordx4 v[216:217], off
	s_waitcnt vmcnt(8)
	s_waitcnt lgkmcnt(0)
	s_barrier
	s_setprio 1
	s_waitcnt lgkmcnt(0)
	v_mfma_f32_16x16x32_bf16 v[166:169], v[90:93], v[154:157], v[166:169]
	v_mfma_f32_16x16x32_bf16 v[158:161], v[114:117], v[154:157], v[158:161]
	v_mfma_f32_16x16x32_bf16 v[126:129], v[90:93], v[170:173], v[126:129]
	v_mfma_f32_16x16x32_bf16 v[118:121], v[114:117], v[170:173], v[118:121]
	v_mfma_f32_16x16x32_bf16 v[98:101], v[90:93], v[178:181], v[98:101]
	v_mfma_f32_16x16x32_bf16 v[94:97], v[114:117], v[178:181], v[94:97]
	v_mfma_f32_16x16x32_bf16 v[78:81], v[90:93], v[186:189], v[78:81]
	v_mfma_f32_16x16x32_bf16 v[74:77], v[114:117], v[186:189], v[74:77]
	v_mfma_f32_16x16x32_bf16 v[166:169], v[102:105], v[162:165], v[166:169]
	v_mfma_f32_16x16x32_bf16 v[158:161], v[122:125], v[162:165], v[158:161]
	v_mfma_f32_16x16x32_bf16 v[126:129], v[102:105], v[174:177], v[126:129]
	v_mfma_f32_16x16x32_bf16 v[118:121], v[122:125], v[174:177], v[118:121]
	v_mfma_f32_16x16x32_bf16 v[98:101], v[102:105], v[182:185], v[98:101]
	v_mfma_f32_16x16x32_bf16 v[94:97], v[122:125], v[182:185], v[94:97]
	v_mfma_f32_16x16x32_bf16 v[78:81], v[102:105], v[190:193], v[78:81]
	v_mfma_f32_16x16x32_bf16 v[74:77], v[122:125], v[190:193], v[74:77]
	v_mfma_f32_16x16x32_bf16 v[138:141], v[130:133], v[154:157], v[138:141]
	v_mfma_f32_16x16x32_bf16 v[134:137], v[146:149], v[154:157], v[134:137]
	v_mfma_f32_16x16x32_bf16 v[110:113], v[130:133], v[170:173], v[110:113]
	v_mfma_f32_16x16x32_bf16 v[106:109], v[146:149], v[170:173], v[106:109]
	v_mfma_f32_16x16x32_bf16 v[86:89], v[130:133], v[178:181], v[86:89]
	v_mfma_f32_16x16x32_bf16 v[82:85], v[146:149], v[178:181], v[82:85]
	v_mfma_f32_16x16x32_bf16 v[70:73], v[130:133], v[186:189], v[70:73]
	v_mfma_f32_16x16x32_bf16 v[66:69], v[146:149], v[186:189], v[66:69]
	v_mfma_f32_16x16x32_bf16 v[138:141], v[142:145], v[162:165], v[138:141]
	v_mfma_f32_16x16x32_bf16 v[134:137], v[150:153], v[162:165], v[134:137]
	v_mfma_f32_16x16x32_bf16 v[110:113], v[142:145], v[174:177], v[110:113]
	v_mfma_f32_16x16x32_bf16 v[106:109], v[150:153], v[174:177], v[106:109]
	v_mfma_f32_16x16x32_bf16 v[86:89], v[142:145], v[182:185], v[86:89]
	v_mfma_f32_16x16x32_bf16 v[82:85], v[150:153], v[182:185], v[82:85]
	v_mfma_f32_16x16x32_bf16 v[70:73], v[142:145], v[190:193], v[70:73]
	v_mfma_f32_16x16x32_bf16 v[66:69], v[150:153], v[190:193], v[66:69]
	s_setprio 0
	s_barrier
	s_add_i32 s18, s47, s26
	v_lshl_add_u64 v[208:209], v[208:209], 0, s[0:1]
	s_mov_b32 m0, s18
	ds_read_b128 v[154:157], v247 offset:49152
	ds_read_b128 v[162:165], v247 offset:50176
	ds_read_b128 v[170:173], v247 offset:51200
	ds_read_b128 v[174:177], v247 offset:52224
	ds_read_b128 v[178:181], v247 offset:53248
	ds_read_b128 v[182:185], v247 offset:54272
	ds_read_b128 v[186:189], v247 offset:55296
	ds_read_b128 v[190:193], v247 offset:56320
	global_load_lds_dwordx4 v[208:209], off
	s_add_i32 m0, s18, 0x2000
	s_add_u32 s18, s22, 0xb0080
	v_lshl_add_u64 v[208:209], v[210:211], 0, s[0:1]
	s_addc_u32 s19, s23, 0
	s_add_i32 s22, s48, s26
	global_load_lds_dwordx4 v[208:209], off
	v_lshl_add_u64 v[208:209], s[18:19], 0, v[198:199]
	s_mov_b32 m0, s22
	s_nop 0
	global_load_lds_dwordx4 v[208:209], off
	v_lshl_add_u64 v[208:209], s[18:19], 0, v[196:197]
	s_add_i32 m0, s22, 0x2000
	s_nop 0
	global_load_lds_dwordx4 v[208:209], off
	v_lshl_add_u64 v[208:209], v[212:213], 0, s[0:1]
	s_mov_b32 m0, s34
	s_nop 0
	global_load_lds_dwordx4 v[208:209], off
	v_lshl_add_u64 v[208:209], v[214:215], 0, s[0:1]
	s_mov_b32 m0, s35
	s_nop 0
	global_load_lds_dwordx4 v[208:209], off
	s_waitcnt vmcnt(8)
	s_waitcnt lgkmcnt(0)
	s_barrier
	s_setprio 1
	s_waitcnt lgkmcnt(0)
	v_mfma_f32_16x16x32_bf16 v[62:65], v[90:93], v[154:157], v[62:65]
	v_mfma_f32_16x16x32_bf16 v[58:61], v[114:117], v[154:157], v[58:61]
	v_mfma_f32_16x16x32_bf16 v[46:49], v[90:93], v[170:173], v[46:49]
	v_mfma_f32_16x16x32_bf16 v[42:45], v[114:117], v[170:173], v[42:45]
	v_mfma_f32_16x16x32_bf16 v[30:33], v[90:93], v[178:181], v[30:33]
	v_mfma_f32_16x16x32_bf16 v[26:29], v[114:117], v[178:181], v[26:29]
	v_mfma_f32_16x16x32_bf16 v[14:17], v[90:93], v[186:189], v[14:17]
	v_mfma_f32_16x16x32_bf16 v[10:13], v[114:117], v[186:189], v[10:13]
	v_mfma_f32_16x16x32_bf16 v[62:65], v[102:105], v[162:165], v[62:65]
	v_mfma_f32_16x16x32_bf16 v[58:61], v[122:125], v[162:165], v[58:61]
	v_mfma_f32_16x16x32_bf16 v[46:49], v[102:105], v[174:177], v[46:49]
	v_mfma_f32_16x16x32_bf16 v[42:45], v[122:125], v[174:177], v[42:45]
	v_mfma_f32_16x16x32_bf16 v[30:33], v[102:105], v[182:185], v[30:33]
	v_mfma_f32_16x16x32_bf16 v[26:29], v[122:125], v[182:185], v[26:29]
	v_mfma_f32_16x16x32_bf16 v[14:17], v[102:105], v[190:193], v[14:17]
	v_mfma_f32_16x16x32_bf16 v[10:13], v[122:125], v[190:193], v[10:13]
	v_mfma_f32_16x16x32_bf16 v[54:57], v[130:133], v[154:157], v[54:57]
	v_mfma_f32_16x16x32_bf16 v[50:53], v[146:149], v[154:157], v[50:53]
	v_mfma_f32_16x16x32_bf16 v[38:41], v[130:133], v[170:173], v[38:41]
	v_mfma_f32_16x16x32_bf16 v[34:37], v[146:149], v[170:173], v[34:37]
	v_mfma_f32_16x16x32_bf16 v[22:25], v[130:133], v[178:181], v[22:25]
	v_mfma_f32_16x16x32_bf16 v[18:21], v[146:149], v[178:181], v[18:21]
	v_mfma_f32_16x16x32_bf16 v[6:9], v[130:133], v[186:189], v[6:9]
	v_mfma_f32_16x16x32_bf16 v[2:5], v[146:149], v[186:189], v[2:5]
	v_mfma_f32_16x16x32_bf16 v[54:57], v[142:145], v[162:165], v[54:57]
	v_mfma_f32_16x16x32_bf16 v[50:53], v[150:153], v[162:165], v[50:53]
	v_mfma_f32_16x16x32_bf16 v[38:41], v[142:145], v[174:177], v[38:41]
	v_mfma_f32_16x16x32_bf16 v[34:37], v[150:153], v[174:177], v[34:37]
	v_mfma_f32_16x16x32_bf16 v[22:25], v[142:145], v[182:185], v[22:25]
	v_mfma_f32_16x16x32_bf16 v[18:21], v[150:153], v[182:185], v[18:21]
	v_mfma_f32_16x16x32_bf16 v[6:9], v[142:145], v[190:193], v[6:9]
	v_mfma_f32_16x16x32_bf16 v[2:5], v[150:153], v[190:193], v[2:5]
	s_setprio 0
	s_barrier
	s_add_i32 s46, s46, 2
	s_add_u32 s44, s44, 0x100
	s_addc_u32 s45, s45, 0
	s_cmp_gt_u32 s46, 41
	s_mov_b64 s[18:19], s[20:21]
	s_cbranch_scc0 .LBB0_636
	s_and_b64 vcc, exec, s[10:11]
	s_cbranch_vccz .LBB0_639
	s_barrier

.LBB0_688:
	s_add_u32 s20, s44, s18
	s_addc_u32 s21, s45, s19
	s_add_u32 s20, s20, 0x5000100
	s_addc_u32 s21, s21, 0
	s_add_u32 s49, s46, s18
	s_addc_u32 s50, s47, s19
	s_add_i32 s51, 0, 0x10000
	s_cmpk_eq_i32 s18, 0x700
	s_cselect_b32 s23, s39, s21
	s_cselect_b32 s22, s17, s20
	v_add_u32_e32 v144, s51, v148
	s_cselect_b32 s21, s43, s50
	s_cselect_b32 s20, s42, s49
	s_add_i32 s49, 0, 0x14000
	ds_read_b128 v[140:143], v144
	ds_read_b128 v[154:157], v144 offset:1024
	ds_read_b128 v[158:161], v144 offset:2048
	ds_read_b128 v[162:165], v144 offset:3072
	v_add_u32_e32 v144, s49, v148
	ds_read_b128 v[166:169], v144
	ds_read_b128 v[170:173], v144 offset:1024
	ds_read_b128 v[174:177], v144 offset:2048
	ds_read_b128 v[178:181], v144 offset:3072
	v_lshl_add_u64 v[144:145], v[136:137], 0, s[18:19]
	s_add_i32 m0, s24, 0xc000
	ds_read_b128 v[182:185], v152
	ds_read_b128 v[186:189], v152 offset:1024
	ds_read_b128 v[190:193], v152 offset:2048
	ds_read_b128 v[196:199], v152 offset:3072
	ds_read_b128 v[202:205], v152 offset:4096
	ds_read_b128 v[206:209], v152 offset:5120
	ds_read_b128 v[210:213], v152 offset:6144
	ds_read_b128 v[214:217], v152 offset:7168
	global_load_lds_dwordx4 v[144:145], off
	v_lshl_add_u64 v[144:145], v[138:139], 0, s[18:19]
	s_add_i32 m0, s24, 0xe000
	s_nop 0
	global_load_lds_dwordx4 v[144:145], off
	s_waitcnt vmcnt(8)
	s_waitcnt lgkmcnt(0)
	s_barrier
	s_setprio 1
	s_waitcnt lgkmcnt(0)
	v_mfma_f32_16x16x32_bf16 v[126:129], v[140:143], v[182:185], v[126:129]
	v_mfma_f32_16x16x32_bf16 v[122:125], v[158:161], v[182:185], v[122:125]
	v_mfma_f32_16x16x32_bf16 v[110:113], v[140:143], v[190:193], v[110:113]
	v_mfma_f32_16x16x32_bf16 v[106:109], v[158:161], v[190:193], v[106:109]
	v_mfma_f32_16x16x32_bf16 v[94:97], v[140:143], v[202:205], v[94:97]
	v_mfma_f32_16x16x32_bf16 v[90:93], v[158:161], v[202:205], v[90:93]
	v_mfma_f32_16x16x32_bf16 v[78:81], v[140:143], v[210:213], v[78:81]
	v_mfma_f32_16x16x32_bf16 v[74:77], v[158:161], v[210:213], v[74:77]
	v_mfma_f32_16x16x32_bf16 v[126:129], v[154:157], v[186:189], v[126:129]
	v_mfma_f32_16x16x32_bf16 v[122:125], v[162:165], v[186:189], v[122:125]
	v_mfma_f32_16x16x32_bf16 v[110:113], v[154:157], v[196:199], v[110:113]
	v_mfma_f32_16x16x32_bf16 v[106:109], v[162:165], v[196:199], v[106:109]
	v_mfma_f32_16x16x32_bf16 v[94:97], v[154:157], v[206:209], v[94:97]
	v_mfma_f32_16x16x32_bf16 v[90:93], v[162:165], v[206:209], v[90:93]
	v_mfma_f32_16x16x32_bf16 v[78:81], v[154:157], v[214:217], v[78:81]
	v_mfma_f32_16x16x32_bf16 v[74:77], v[162:165], v[214:217], v[74:77]
	v_mfma_f32_16x16x32_bf16 v[118:121], v[166:169], v[182:185], v[118:121]
	v_mfma_f32_16x16x32_bf16 v[114:117], v[174:177], v[182:185], v[114:117]
	v_mfma_f32_16x16x32_bf16 v[102:105], v[166:169], v[190:193], v[102:105]
	v_mfma_f32_16x16x32_bf16 v[98:101], v[174:177], v[190:193], v[98:101]
	v_mfma_f32_16x16x32_bf16 v[86:89], v[166:169], v[202:205], v[86:89]
	v_mfma_f32_16x16x32_bf16 v[82:85], v[174:177], v[202:205], v[82:85]
	v_mfma_f32_16x16x32_bf16 v[70:73], v[166:169], v[210:213], v[70:73]
	v_mfma_f32_16x16x32_bf16 v[66:69], v[174:177], v[210:213], v[66:69]
	v_mfma_f32_16x16x32_bf16 v[118:121], v[170:173], v[186:189], v[118:121]
	v_mfma_f32_16x16x32_bf16 v[114:117], v[178:181], v[186:189], v[114:117]
	v_mfma_f32_16x16x32_bf16 v[102:105], v[170:173], v[196:199], v[102:105]
	v_mfma_f32_16x16x32_bf16 v[98:101], v[178:181], v[196:199], v[98:101]
	v_mfma_f32_16x16x32_bf16 v[86:89], v[170:173], v[206:209], v[86:89]
	v_mfma_f32_16x16x32_bf16 v[82:85], v[178:181], v[206:209], v[82:85]
	v_mfma_f32_16x16x32_bf16 v[70:73], v[170:173], v[214:217], v[70:73]
	v_mfma_f32_16x16x32_bf16 v[66:69], v[178:181], v[214:217], v[66:69]
	s_setprio 0
	s_barrier
	s_cmp_eq_u32 s99, 0
	s_cbranch_scc1 .Lbgc_it_skip
	s_mov_b64 exec, s[100:101]
	s_nop 0
	global_store_dwordx4 v[230:231], v[232:235], off nt
	s_mov_b64 exec, -1
	v_add_u32_e32 v226, 64, v226
	v_add_u32_e32 v227, 1, v227
	v_cmp_le_i32_e32 vcc, 0x1ffc0, v226
	v_subrev_u32_e32 v236, 0x1ffc0, v226
	s_nop 0
	v_cndmask_b32_e32 v226, v226, v236, vcc
	v_cndmask_b32_e64 v238, 0, 1, vcc
	v_add_u32_e32 v227, v227, v238
	v_mov_b32_e32 v236, 0x200400
	v_mov_b32_e32 v238, 0x200800
	v_cndmask_b32_e32 v236, v236, v238, vcc
	v_lshl_add_u64 v[228:229], v[228:229], 0, v[236:237]
	v_lshl_add_u64 v[230:231], v[230:231], 0, v[236:237]
	v_cmp_gt_i32_e32 vcc, 64, v227
	s_nop 1
	s_mov_b64 s[100:101], vcc
	s_mov_b64 exec, vcc
	s_nop 0
	global_load_dwordx4 v[232:235], v[228:229], off nt
	s_mov_b64 exec, -1
	s_cmp_lg_u64 s[100:101], 0
	s_cselect_b32 s99, 1, 0
.Lbgc_it_skip:
	s_add_i32 s50, s51, s2
	v_lshl_add_u64 v[144:145], s[20:21], 0, v[0:1]
	s_mov_b32 m0, s50
	ds_read_b128 v[182:185], v152 offset:16384
	ds_read_b128 v[186:189], v152 offset:17408
	ds_read_b128 v[190:193], v152 offset:18432
	ds_read_b128 v[196:199], v152 offset:19456
	ds_read_b128 v[202:205], v152 offset:20480
	ds_read_b128 v[206:209], v152 offset:21504
	ds_read_b128 v[210:213], v152 offset:22528
	ds_read_b128 v[214:217], v152 offset:23552
	global_load_lds_dwordx4 v[144:145], off
	s_add_i32 m0, s50, 0x2000
	s_add_u32 s50, s20, 0x40000
	v_lshl_add_u64 v[218:219], s[20:21], 0, v[130:131]
	s_addc_u32 s51, s21, 0
	s_add_i32 s49, s49, s2
	global_load_lds_dwordx4 v[218:219], off
	v_lshl_add_u64 v[220:221], s[50:51], 0, v[0:1]
	s_mov_b32 m0, s49
	v_lshl_add_u64 v[222:223], s[22:23], 0, v[130:131]
	global_load_lds_dwordx4 v[220:221], off
	v_lshl_add_u64 v[220:221], s[50:51], 0, v[130:131]
	s_add_i32 m0, s49, 0x2000
	s_nop 0
	global_load_lds_dwordx4 v[220:221], off
	v_lshl_add_u64 v[220:221], s[22:23], 0, v[0:1]
	s_mov_b32 m0, s24
	s_nop 0
	global_load_lds_dwordx4 v[220:221], off
	s_mov_b32 m0, s25
	s_nop 0
	global_load_lds_dwordx4 v[222:223], off
	s_waitcnt vmcnt(8)
	s_waitcnt lgkmcnt(0)
	s_barrier
	s_setprio 1
	s_waitcnt lgkmcnt(0)
	v_mfma_f32_16x16x32_bf16 v[62:65], v[140:143], v[182:185], v[62:65]
	v_mfma_f32_16x16x32_bf16 v[58:61], v[158:161], v[182:185], v[58:61]
	v_mfma_f32_16x16x32_bf16 v[46:49], v[140:143], v[190:193], v[46:49]
	v_mfma_f32_16x16x32_bf16 v[42:45], v[158:161], v[190:193], v[42:45]
	v_mfma_f32_16x16x32_bf16 v[30:33], v[140:143], v[202:205], v[30:33]
	v_mfma_f32_16x16x32_bf16 v[26:29], v[158:161], v[202:205], v[26:29]
	v_mfma_f32_16x16x32_bf16 v[14:17], v[140:143], v[210:213], v[14:17]
	v_mfma_f32_16x16x32_bf16 v[10:13], v[158:161], v[210:213], v[10:13]
	v_mfma_f32_16x16x32_bf16 v[62:65], v[154:157], v[186:189], v[62:65]
	v_mfma_f32_16x16x32_bf16 v[58:61], v[162:165], v[186:189], v[58:61]
	v_mfma_f32_16x16x32_bf16 v[46:49], v[154:157], v[196:199], v[46:49]
	v_mfma_f32_16x16x32_bf16 v[42:45], v[162:165], v[196:199], v[42:45]
	v_mfma_f32_16x16x32_bf16 v[30:33], v[154:157], v[206:209], v[30:33]
	v_mfma_f32_16x16x32_bf16 v[26:29], v[162:165], v[206:209], v[26:29]
	v_mfma_f32_16x16x32_bf16 v[14:17], v[154:157], v[214:217], v[14:17]
	v_mfma_f32_16x16x32_bf16 v[10:13], v[162:165], v[214:217], v[10:13]
	v_mfma_f32_16x16x32_bf16 v[54:57], v[166:169], v[182:185], v[54:57]
	v_mfma_f32_16x16x32_bf16 v[50:53], v[174:177], v[182:185], v[50:53]
	v_mfma_f32_16x16x32_bf16 v[38:41], v[166:169], v[190:193], v[38:41]
	v_mfma_f32_16x16x32_bf16 v[34:37], v[174:177], v[190:193], v[34:37]
	v_mfma_f32_16x16x32_bf16 v[22:25], v[166:169], v[202:205], v[22:25]
	v_mfma_f32_16x16x32_bf16 v[18:21], v[174:177], v[202:205], v[18:21]
	v_mfma_f32_16x16x32_bf16 v[6:9], v[166:169], v[210:213], v[6:9]
	v_mfma_f32_16x16x32_bf16 v[2:5], v[174:177], v[210:213], v[2:5]
	v_mfma_f32_16x16x32_bf16 v[54:57], v[170:173], v[186:189], v[54:57]
	v_mfma_f32_16x16x32_bf16 v[50:53], v[178:181], v[186:189], v[50:53]
	v_mfma_f32_16x16x32_bf16 v[38:41], v[170:173], v[196:199], v[38:41]
	v_mfma_f32_16x16x32_bf16 v[34:37], v[178:181], v[196:199], v[34:37]
	v_mfma_f32_16x16x32_bf16 v[22:25], v[170:173], v[206:209], v[22:25]
	v_mfma_f32_16x16x32_bf16 v[18:21], v[178:181], v[206:209], v[18:21]
	v_mfma_f32_16x16x32_bf16 v[6:9], v[170:173], v[214:217], v[6:9]
	v_mfma_f32_16x16x32_bf16 v[2:5], v[178:181], v[214:217], v[2:5]
	s_setprio 0
	s_barrier
	s_add_i32 s49, 0, 0x18000
	v_add_u32_e32 v153, s49, v148
	s_add_i32 s50, 0, 0x1c000
	ds_read_b128 v[140:143], v153
	ds_read_b128 v[154:157], v153 offset:1024
	ds_read_b128 v[158:161], v153 offset:2048
	ds_read_b128 v[162:165], v153 offset:3072
	v_add_u32_e32 v153, s50, v148
	ds_read_b128 v[166:169], v153
	ds_read_b128 v[170:173], v153 offset:1024
	ds_read_b128 v[174:177], v153 offset:2048
	ds_read_b128 v[178:181], v153 offset:3072
	s_add_u32 s22, s22, 0x40000
	s_addc_u32 s23, s23, 0
	s_mov_b32 m0, s26
	v_lshl_add_u64 v[224:225], s[22:23], 0, v[0:1]
	ds_read_b128 v[182:185], v152 offset:32768
	ds_read_b128 v[186:189], v152 offset:33792
	ds_read_b128 v[190:193], v152 offset:34816
	ds_read_b128 v[196:199], v152 offset:35840
	ds_read_b128 v[202:205], v152 offset:36864
	ds_read_b128 v[206:209], v152 offset:37888
	ds_read_b128 v[210:213], v152 offset:38912
	ds_read_b128 v[214:217], v152 offset:39936
	global_load_lds_dwordx4 v[224:225], off
	v_lshl_add_u64 v[224:225], s[22:23], 0, v[130:131]
	s_mov_b32 m0, s27
	s_nop 0
	global_load_lds_dwordx4 v[224:225], off
	s_waitcnt vmcnt(8)
	s_waitcnt lgkmcnt(0)
	s_barrier
	s_setprio 1
	s_waitcnt lgkmcnt(0)
	v_mfma_f32_16x16x32_bf16 v[126:129], v[140:143], v[182:185], v[126:129]
	v_mfma_f32_16x16x32_bf16 v[122:125], v[158:161], v[182:185], v[122:125]
	v_mfma_f32_16x16x32_bf16 v[110:113], v[140:143], v[190:193], v[110:113]
	v_mfma_f32_16x16x32_bf16 v[106:109], v[158:161], v[190:193], v[106:109]
	v_mfma_f32_16x16x32_bf16 v[94:97], v[140:143], v[202:205], v[94:97]
	v_mfma_f32_16x16x32_bf16 v[90:93], v[158:161], v[202:205], v[90:93]
	v_mfma_f32_16x16x32_bf16 v[78:81], v[140:143], v[210:213], v[78:81]
	v_mfma_f32_16x16x32_bf16 v[74:77], v[158:161], v[210:213], v[74:77]
	v_mfma_f32_16x16x32_bf16 v[126:129], v[154:157], v[186:189], v[126:129]
	v_mfma_f32_16x16x32_bf16 v[122:125], v[162:165], v[186:189], v[122:125]
	v_mfma_f32_16x16x32_bf16 v[110:113], v[154:157], v[196:199], v[110:113]
	v_mfma_f32_16x16x32_bf16 v[106:109], v[162:165], v[196:199], v[106:109]
	v_mfma_f32_16x16x32_bf16 v[94:97], v[154:157], v[206:209], v[94:97]
	v_mfma_f32_16x16x32_bf16 v[90:93], v[162:165], v[206:209], v[90:93]
	v_mfma_f32_16x16x32_bf16 v[78:81], v[154:157], v[214:217], v[78:81]
	v_mfma_f32_16x16x32_bf16 v[74:77], v[162:165], v[214:217], v[74:77]
	v_mfma_f32_16x16x32_bf16 v[118:121], v[166:169], v[182:185], v[118:121]
	v_mfma_f32_16x16x32_bf16 v[114:117], v[174:177], v[182:185], v[114:117]
	v_mfma_f32_16x16x32_bf16 v[102:105], v[166:169], v[190:193], v[102:105]
	v_mfma_f32_16x16x32_bf16 v[98:101], v[174:177], v[190:193], v[98:101]
	v_mfma_f32_16x16x32_bf16 v[86:89], v[166:169], v[202:205], v[86:89]
	v_mfma_f32_16x16x32_bf16 v[82:85], v[174:177], v[202:205], v[82:85]
	v_mfma_f32_16x16x32_bf16 v[70:73], v[166:169], v[210:213], v[70:73]
	v_mfma_f32_16x16x32_bf16 v[66:69], v[174:177], v[210:213], v[66:69]
	v_mfma_f32_16x16x32_bf16 v[118:121], v[170:173], v[186:189], v[118:121]
	v_mfma_f32_16x16x32_bf16 v[114:117], v[178:181], v[186:189], v[114:117]
	v_mfma_f32_16x16x32_bf16 v[102:105], v[170:173], v[196:199], v[102:105]
	v_mfma_f32_16x16x32_bf16 v[98:101], v[178:181], v[196:199], v[98:101]
	v_mfma_f32_16x16x32_bf16 v[86:89], v[170:173], v[206:209], v[86:89]
	v_mfma_f32_16x16x32_bf16 v[82:85], v[178:181], v[206:209], v[82:85]
	v_mfma_f32_16x16x32_bf16 v[70:73], v[170:173], v[214:217], v[70:73]
	v_mfma_f32_16x16x32_bf16 v[66:69], v[178:181], v[214:217], v[66:69]
	s_setprio 0
	s_barrier
	s_add_i32 s22, s49, s2
	v_lshl_add_u64 v[144:145], v[144:145], 0, s[0:1]
	s_mov_b32 m0, s22
	ds_read_b128 v[182:185], v152 offset:49152
	ds_read_b128 v[186:189], v152 offset:50176
	ds_read_b128 v[190:193], v152 offset:51200
	ds_read_b128 v[196:199], v152 offset:52224
	ds_read_b128 v[202:205], v152 offset:53248
	ds_read_b128 v[206:209], v152 offset:54272
	ds_read_b128 v[210:213], v152 offset:55296
	ds_read_b128 v[214:217], v152 offset:56320
	global_load_lds_dwordx4 v[144:145], off
	s_add_i32 m0, s22, 0x2000
	s_add_u32 s20, s20, 0x40080
	v_lshl_add_u64 v[144:145], v[218:219], 0, s[0:1]
	s_addc_u32 s21, s21, 0
	s_add_i32 s22, s50, s2
	global_load_lds_dwordx4 v[144:145], off
	v_lshl_add_u64 v[144:145], s[20:21], 0, v[0:1]
	s_mov_b32 m0, s22
	s_nop 0
	global_load_lds_dwordx4 v[144:145], off
	v_lshl_add_u64 v[144:145], s[20:21], 0, v[130:131]
	s_add_i32 m0, s22, 0x2000
	s_nop 0
	global_load_lds_dwordx4 v[144:145], off
	v_lshl_add_u64 v[144:145], v[220:221], 0, s[0:1]
	s_mov_b32 m0, s28
	s_nop 0
	global_load_lds_dwordx4 v[144:145], off
	v_lshl_add_u64 v[144:145], v[222:223], 0, s[0:1]
	s_mov_b32 m0, s29
	s_nop 0
	global_load_lds_dwordx4 v[144:145], off
	s_waitcnt vmcnt(8)
	s_waitcnt lgkmcnt(0)
	s_barrier
	s_setprio 1
	s_waitcnt lgkmcnt(0)
	v_mfma_f32_16x16x32_bf16 v[62:65], v[140:143], v[182:185], v[62:65]
	v_mfma_f32_16x16x32_bf16 v[58:61], v[158:161], v[182:185], v[58:61]
	v_mfma_f32_16x16x32_bf16 v[46:49], v[140:143], v[190:193], v[46:49]
	v_mfma_f32_16x16x32_bf16 v[42:45], v[158:161], v[190:193], v[42:45]
	v_mfma_f32_16x16x32_bf16 v[30:33], v[140:143], v[202:205], v[30:33]
	v_mfma_f32_16x16x32_bf16 v[26:29], v[158:161], v[202:205], v[26:29]
	v_mfma_f32_16x16x32_bf16 v[14:17], v[140:143], v[210:213], v[14:17]
	v_mfma_f32_16x16x32_bf16 v[10:13], v[158:161], v[210:213], v[10:13]
	v_mfma_f32_16x16x32_bf16 v[62:65], v[154:157], v[186:189], v[62:65]
	v_mfma_f32_16x16x32_bf16 v[58:61], v[162:165], v[186:189], v[58:61]
	v_mfma_f32_16x16x32_bf16 v[46:49], v[154:157], v[196:199], v[46:49]
	v_mfma_f32_16x16x32_bf16 v[42:45], v[162:165], v[196:199], v[42:45]
	v_mfma_f32_16x16x32_bf16 v[30:33], v[154:157], v[206:209], v[30:33]
	v_mfma_f32_16x16x32_bf16 v[26:29], v[162:165], v[206:209], v[26:29]
	v_mfma_f32_16x16x32_bf16 v[14:17], v[154:157], v[214:217], v[14:17]
	v_mfma_f32_16x16x32_bf16 v[10:13], v[162:165], v[214:217], v[10:13]
	v_mfma_f32_16x16x32_bf16 v[54:57], v[166:169], v[182:185], v[54:57]
	v_mfma_f32_16x16x32_bf16 v[50:53], v[174:177], v[182:185], v[50:53]
	v_mfma_f32_16x16x32_bf16 v[38:41], v[166:169], v[190:193], v[38:41]
	v_mfma_f32_16x16x32_bf16 v[34:37], v[174:177], v[190:193], v[34:37]
	v_mfma_f32_16x16x32_bf16 v[22:25], v[166:169], v[202:205], v[22:25]
	v_mfma_f32_16x16x32_bf16 v[18:21], v[174:177], v[202:205], v[18:21]
	v_mfma_f32_16x16x32_bf16 v[6:9], v[166:169], v[210:213], v[6:9]
	v_mfma_f32_16x16x32_bf16 v[2:5], v[174:177], v[210:213], v[2:5]
	v_mfma_f32_16x16x32_bf16 v[54:57], v[170:173], v[186:189], v[54:57]
	v_mfma_f32_16x16x32_bf16 v[50:53], v[178:181], v[186:189], v[50:53]
	v_mfma_f32_16x16x32_bf16 v[38:41], v[170:173], v[196:199], v[38:41]
	v_mfma_f32_16x16x32_bf16 v[34:37], v[178:181], v[196:199], v[34:37]
	v_mfma_f32_16x16x32_bf16 v[22:25], v[170:173], v[206:209], v[22:25]
	v_mfma_f32_16x16x32_bf16 v[18:21], v[178:181], v[206:209], v[18:21]
	v_mfma_f32_16x16x32_bf16 v[6:9], v[170:173], v[214:217], v[6:9]
	v_mfma_f32_16x16x32_bf16 v[2:5], v[178:181], v[214:217], v[2:5]
	s_setprio 0
	s_barrier
	s_add_i32 s48, s48, 2
	s_add_u32 s18, s18, 0x100
	s_addc_u32 s19, s19, 0
	s_cmp_gt_u32 s48, 13
	s_cbranch_scc0 .LBB0_688
	s_and_b64 vcc, exec, s[8:9]
	s_cbranch_vccz .LBB0_691
	s_barrier
